# combined: streaming loop, early unit loads, P8 piece/mid/final epilogue hoists, P7 hoist, hand-written P2 w_in conversion, chain table DMA spread over waves
# speedup vs baseline: 1.0034x; 1.0034x over previous
; #define CH_BAR() do { asm volatile("s_waitcnt lgkmcnt(0)" ::: "memory"); __builtin_amdgcn_s_barrier(); asm volatile("" ::: "memory"); } while (0)
; #define CH_LD_SC(c_) do { if (wv == 0) { _Pragma("unroll") for (int i = 0; i < 6; ++i) \
;         __builtin_amdgcn_global_load_lds((const unsigned*)(SCT + (c_) * 384 + 64 * i + lane), (LAS unsigned*)(L + CH5_SC + ((c_) & 1) * 1536 + i * 256), 4, 0, 0); } } while (0)
; __device__ __forceinline__ void mlstm_chain_unit(Frame& F, const Args& a, int bh, int slice) {
;     ...
;         CH_BAR();
;         CH_LD_SC(c + 1); CH_DMA_QK(c + 1);
.LBB0_907:
	s_waitcnt lgkmcnt(0)
	s_barrier
	s_mov_b32 s11, s30
	s_andn2_b64 vcc, exec, s[72:73]
	s_add_i32 s30, s30, 1
	v_readlane_b32 s80, v245, 41
	s_bitcmp1_b32 s30, 0
	s_cselect_b32 s10, 0x600, 0
	v_lshl_add_u64 v[66:67], s[34:35], 0, v[186:187]
	s_add_i32 s10, s10, 0
	s_nop 1
	s_cmp_gt_u32 s80, 5
	s_cbranch_scc1 .LBB0_909
	s_lshl_b32 s81, s80, 8
	s_add_i32 s10, s10, s81
	s_add_u32 s80, s81, 0x3cb00600
	s_mov_b32 s81, 0
	s_waitcnt lgkmcnt(0)
	v_lshl_add_u64 v[68:69], v[66:67], 0, s[80:81]
	s_add_i32 m0, s10, 0x24800
	s_nop 0
	global_load_lds_dword v[68:69], off
